# attention queues LPT-like order with T1=32
# baseline (speedup 1.0000x reference)
; __device__ __forceinline__ int fresh_lane() { int l; asm volatile("v_mbcnt_lo_u32_b32 %0, -1, 0\n\tv_mbcnt_hi_u32_b32 %0, -1, %0" : "=v"(l)); return l; }
; #define SEAM(k) do { if (IN(k) && IN((k) + 1)) xcd_barrier(bar, C.wave); } while (0)
; #define PH5 { phase_attention(P, C, (P.pad >> 8) & 3, P.li); }
; #define RUN(k, BODY) do { if (IN(k)) { unsigned char* ws = P.ws; LAUNDER_GPTR(ws); BODY } } while (0)
; __device__ __forceinline__ void phase_attention(const Params& P, const Ctx& C, int parts, int qset) {
;     ...
;     for (int i = 0; i < 8; ++i) { const int x = (x0 + i) & 7;
;         for (;;) {
;             __syncthreads();
;             if (C.wave == 0 && fresh_lane() == 0) *slot = __hip_atomic_fetch_add(qc + 64 * x, 1u, __ATOMIC_RELAXED, __HIP_MEMORY_SCOPE_AGENT);
;             __syncthreads();
;             const unsigned u = *slot;
;             if (u >= 128u) break;
;             const int us = __builtin_amdgcn_readfirstlane((int)u);
; __global__ void __launch_bounds__(NWAVES * 64, 2) fwd_kernel(Params P) {
;     ...
;     RUN(3, PH3); SEAM(3);
;     RUN(4, PH4);
;     RUN(5, PH5); SEAM(5);
.LBB0_1136:
	s_bitcmp1_b32 s101, 1
	s_cbranch_scc1 .Lmy_e7
	s_bitset1_b32 s101, 1
	s_cmpk_lg_i32 s68, 0x100
	s_cbranch_scc1 .Lmy_e7
	s_bitset1_b32 s101, 3
	v_readlane_b32 s99, v254, 10
	s_cmpk_lt_u32 s99, 192
	s_cbranch_scc1 .Lmy_e7
	s_and_b32 s100, s99, 31
	s_mul_i32 s100, s100, 3
	s_add_i32 s100, s100, 32
	s_bitset1_b32 s101, 0
	s_waitcnt vmcnt(0)
	s_barrier
	s_mov_b64 s[2:3], -1
	s_branch .LBB0_1192

; __device__ __forceinline__ int fresh_lane() { int l; asm volatile("v_mbcnt_lo_u32_b32 %0, -1, 0\n\tv_mbcnt_hi_u32_b32 %0, -1, %0" : "=v"(l)); return l; }
; __device__ __forceinline__ void phase_attention(const Params& P, const Ctx& C, int parts, int qset) {
;     ...
;             __syncthreads();
;             if (C.wave == 0 && fresh_lane() == 0) *slot = __hip_atomic_fetch_add(qc + 64 * x, 1u, __ATOMIC_RELAXED, __HIP_MEMORY_SCOPE_AGENT);
;             __syncthreads();
;             const unsigned u = *slot;
;             if (u >= 128u) break;
;             const int us = __builtin_amdgcn_readfirstlane((int)u);
;             int pq = -1, dq = -1;
;             if (us < 96) { const int k = us / 3, r = us - 3 * k; if (r == 0) pq = 63 - k; else dq = 2 * k + r - 1; } else pq = 127 - us;
.LBB0_1208:
	s_waitcnt lgkmcnt(0)
	s_barrier
	ds_read_b32 v0, v218
	s_movk_i32 s2, 0x7f
	s_waitcnt lgkmcnt(0)
	v_cmp_lt_u32_e32 vcc, s2, v0
	s_mov_b64 s[2:3], -1
	s_cbranch_vccnz .LBB0_1201
	v_readfirstlane_b32 s5, v0
	s_cmpk_gt_i32 s5, 127
	s_cbranch_scc1 .LBB0_1213
	s_andn2_b64 vcc, exec, s[2:3]
	s_mov_b32 s4, -1
	s_cbranch_vccz .LBB0_1214

; __device__ __forceinline__ void phase_attention(const Params& P, const Ctx& C, int parts, int qset) {
;     ...
;             const int us = __builtin_amdgcn_readfirstlane((int)u);
;             int pq = -1, dq = -1;
;             if (us < 96) { const int k = us / 3, r = us - 3 * k; if (r == 0) pq = 63 - k; else dq = 2 * k + r - 1; } else pq = 127 - us;
;             if (pq >= 0) { if (parts & 1) { if (fixed_ok) attn_prompt_unit<true>(P, C, x, pq); else attn_prompt_unit<false>(P, C, x, pq); } }
.LBB0_1214:
	s_sub_i32 s3, s5, 32
	s_mul_hi_i32 s2, s3, 0x55555556
	s_mul_i32 s4, s2, -3
	s_add_i32 s4, s4, s3
	s_lshl_b32 s64, s2, 1
	s_add_i32 s64, s64, s4
	s_sub_i32 s2, 31, s2
	s_cmp_eq_u32 s4, 2
	s_cselect_b32 s2, s2, -1
	s_cselect_b32 s4, -1, s64
	s_sub_i32 s3, 63, s5
	s_cmpk_lt_i32 s5, 32
	s_cselect_b32 s64, s3, s2
	s_cselect_b32 s4, -1, s4
	s_cmp_lt_i32 s64, 0
	s_mov_b64 s[2:3], -1
	s_cbranch_scc0 .LBB0_1212
